# attention slc/win loops: next-tile LDS-DMA issued with scalar base + 32-bit lane offset (no 64-bit VALU address math, no exec-mask juggling); on top of v30
# speedup vs baseline: 1.0109x; 1.0109x over previous
.LBB0_1975:
	v_add_u32_e32 v0, 1, v68
	v_lshrrev_b64 v[66:67], v0, v[130:131]
	v_cmp_eq_u64_e64 s[6:7], 0, v[66:67]
	v_ffbl_b32_e32 v67, v67
	v_add_u32_e32 v67, 32, v67
	v_ffbl_b32_e32 v66, v66
	v_cmp_lt_u32_e32 vcc, 62, v68
	v_min_u32_e32 v66, v66, v67
	s_waitcnt vmcnt(0)
	v_add_u32_e32 v157, v0, v66
	s_or_b64 s[6:7], vcc, s[6:7]
	v_cndmask_b32_e64 v0, v157, -1, s[6:7]
	v_cmp_gt_i32_e64 s[6:7], 0, v0
	s_mov_b64 s[8:9], 0
	s_barrier
	v_readfirstlane_b32 s100, v0
	s_lshl_b32 s12, s53, 14
	s_xor_b32 s12, s12, 0x4000
	s_add_i32 s13, s47, s12
	s_cmp_lt_i32 s100, 0
	s_cbranch_scc1 .Lsd_nb
	s_lshl_b32 s100, s100, 14
	s_add_u32 s8, s14, s100
	s_addc_u32 s9, s15, 0
	s_add_u32 s10, s16, s100
	s_addc_u32 s11, s17, 0
	s_add_i32 m0, s13, 0x8000
	s_nop 0
	global_load_lds_dwordx4 v172, s[8:9]
	s_add_i32 m0, s13, 0x8400
	s_nop 0
	global_load_lds_dwordx4 v176, s[8:9]
	s_branch .Lsd_v
.Lsd_nb:
	s_cmp_eq_u64 s[40:41], 0
	s_cbranch_scc1 .Lsd_done
	s_mov_b64 s[10:11], s[42:43]
	s_add_i32 m0, s13, 0x8000
	s_nop 0
	global_load_lds_dwordx4 v[132:133], off
	s_add_i32 m0, s13, 0x8400
	s_nop 0
	global_load_lds_dwordx4 v[134:135], off
.Lsd_v:
	s_mov_b32 m0, s13
	s_nop 0
	global_load_lds_dwordx4 v174, s[10:11]
	s_add_i32 m0, s13, 0x400
	s_nop 0
	global_load_lds_dwordx4 v178, s[10:11]
.Lsd_done:
	v_lshlrev_b32_e64 v0, v68, 1
	v_and_b32_e32 v0, v0, v154
	v_lshlrev_b32_e32 v180, 6, v68
	v_cmp_eq_u32_e32 vcc, 0, v0
	v_cmp_ne_u32_e64 s[10:11], 0, v0
	v_sub_u32_e32 v0, s54, v180
	v_sub_u32_e32 v66, s60, v180
	s_movk_i32 s8, 0x7f
	s_lshl_b32 s20, s53, 14
	v_cmp_lt_i32_e64 s[12:13], s8, v0
	v_cmp_gt_i32_e64 s[8:9], 2.0, v66
	s_add_i32 s62, s20, 0
	s_and_b64 s[12:13], s[12:13], s[8:9]
	s_and_saveexec_b64 s[44:45], s[12:13]
	s_xor_b64 s[12:13], exec, s[44:45]
	s_cbranch_execz .LBB0_1988
	v_mov_b32_e32 v0, s52
	ds_read_b32 v0, v0 offset:512
	v_add_u32_e32 v66, s62, v137
	v_add_u32_e32 v74, v66, v138
	v_add_u32_e32 v75, v66, v140
	v_add_u32_e32 v76, v66, v141
	v_add_u32_e32 v77, v66, v142
	ds_read_b128 v[66:69], v74 offset:32768
	ds_read_b128 v[70:73], v74 offset:40960
	ds_read_b128 v[194:197], v75 offset:32768
	ds_read_b128 v[202:205], v75 offset:40960
	ds_read_b128 v[210:213], v76 offset:32768
	ds_read_b128 v[218:221], v76 offset:40960
	ds_read_b128 v[226:229], v77 offset:32768
	ds_read_b128 v[234:237], v77 offset:40960
	v_xor_b32_e32 v158, 0x80, v74
	ds_read_b128 v[158:161], v158 offset:32768
	v_xor_b32_e32 v164, 0x80, v74
	ds_read_b128 v[164:167], v164 offset:40960
	v_xor_b32_e32 v198, 0x80, v75
	ds_read_b128 v[198:201], v198 offset:32768
	v_xor_b32_e32 v206, 0x80, v75
	ds_read_b128 v[206:209], v206 offset:40960
	v_xor_b32_e32 v214, 0x80, v76
	ds_read_b128 v[214:217], v214 offset:32768
	v_xor_b32_e32 v222, 0x80, v76
	ds_read_b128 v[222:225], v222 offset:40960
	v_xor_b32_e32 v230, 0x80, v77
	ds_read_b128 v[230:233], v230 offset:32768
	v_xor_b32_e32 v238, 0x80, v77
	ds_read_b128 v[238:241], v238 offset:40960
	s_waitcnt lgkmcnt(8)
	v_mfma_f32_32x32x16_bf16 v[82:97], v[66:69], v[98:101], 0
	v_mfma_f32_32x32x16_bf16 v[66:81], v[70:73], v[98:101], 0
	v_mfma_f32_32x32x16_bf16 v[82:97], v[194:197], v[102:105], v[82:97]
	v_mfma_f32_32x32x16_bf16 v[66:81], v[202:205], v[102:105], v[66:81]
	v_mfma_f32_32x32x16_bf16 v[82:97], v[210:213], v[106:109], v[82:97]
	v_mfma_f32_32x32x16_bf16 v[66:81], v[218:221], v[106:109], v[66:81]
	v_mfma_f32_32x32x16_bf16 v[82:97], v[226:229], v[110:113], v[82:97]
	v_mfma_f32_32x32x16_bf16 v[66:81], v[234:237], v[110:113], v[66:81]
	s_waitcnt lgkmcnt(0)
	v_mfma_f32_32x32x16_bf16 v[82:97], v[158:161], v[114:117], v[82:97]
	v_mfma_f32_32x32x16_bf16 v[66:81], v[164:167], v[114:117], v[66:81]
	v_mfma_f32_32x32x16_bf16 v[82:97], v[198:201], v[118:121], v[82:97]
	v_mfma_f32_32x32x16_bf16 v[66:81], v[206:209], v[118:121], v[66:81]
	v_mfma_f32_32x32x16_bf16 v[82:97], v[214:217], v[122:125], v[82:97]
	v_mfma_f32_32x32x16_bf16 v[66:81], v[222:225], v[122:125], v[66:81]
	v_mfma_f32_32x32x16_bf16 v[82:97], v[230:233], v[126:129], v[82:97]
	v_mfma_f32_32x32x16_bf16 v[66:81], v[238:241], v[126:129], v[66:81]
	v_sub_f32_e32 v0, v0, v153
	v_cndmask_b32_e64 v0, v186, v0, s[10:11]

.LBB0_1999:
	s_andn2_b64 vcc, exec, s[8:9]
	s_cbranch_vccnz .LBB0_2001
	v_readfirstlane_b32 s100, v66
	s_lshl_b64 s[8:9], s[20:21], 14
	s_xor_b32 s100, s100, 0x4000
	s_add_i32 s13, s47, s100
	s_add_u32 s10, s55, s8
	s_addc_u32 s11, s57, s9
	s_add_u32 s8, s58, s8
	s_addc_u32 s9, s59, s9
	s_add_i32 m0, s13, 0x8000
	s_nop 0
	global_load_lds_dwordx4 v172, s[10:11]
	s_add_i32 m0, s13, 0x8400
	s_nop 0
	global_load_lds_dwordx4 v176, s[10:11]
	s_mov_b32 m0, s13
	s_nop 0
	global_load_lds_dwordx4 v174, s[8:9]
	s_add_i32 m0, s13, 0x400
	s_nop 0
	global_load_lds_dwordx4 v178, s[8:9]
	v_mov_b32_e32 v133, v66
